# dilated-attention tile loop: softmax (scale folded into exp via pk_fma, exp, bf16 pack, row-sum) interleaved with the PV MFMAs per 16-key pack instead of running before them
# speedup vs baseline: 1.0105x; 1.0073x over previous
; #define LAS __attribute__((address_space(3)))
; #define MFMA32(a, b, c) __builtin_amdgcn_mfma_f32_32x32x16_bf16((a), (b), (c), 0, 0, 0)
; template <int KSTEPS, class Pol>
; __device__ __forceinline__ void attn_pass(LAS unsigned char* lds, const Pol& P, const bf16_t* qb, int ldq, const bf16_t* kb, int ldk, const bf16_t* vb, int ldv,
;                                           float qs, f32x16 (&O)[4], float& m, float& l) {
;     ...
;     auto qk_softmax = [&](int st, int t) __attribute__((always_inline)) {
;         LAS unsigned char* Kb = lds + st * A_STAGE + krow;
;         f32x16 S0, S1;
;         P.fill(S0, S1, qi, half, t, wave);
; #pragma unroll
;         for (int ks = 0; ks < KSTEPS; ++ks) {
;             const int so = ((2 * ks) ^ kx) << 4;
;             const bf16x8 a0 = *(const LAS bf16x8*)(Kb + so);
;             const bf16x8 a1 = *(const LAS bf16x8*)(Kb + 32 * KROWB + so);
;             S0 = MFMA32(a0, qf[ks], S0);
;             S1 = MFMA32(a1, qf[ks], S1);
;         }
;         S0 = S0 * qs; S1 = S1 * qs;
;         float mx = fmaxf(S0[0], S1[0]);
; #pragma unroll
;         for (int i = 1; i < 16; ++i) mx = fmaxf(fmaxf(mx, S0[i]), S1[i]);
;         mx = fmaxf(mx, __shfl_xor(mx, 32));
;         const float mnew = fmaxf(m, mx);
;         const float alpha = __builtin_amdgcn_exp2f(m - mnew);
;         m = mnew;
.LBB0_237:
	s_lshl_b32 s44, s74, 15
	s_add_i32 s44, s44, 0
	v_add_u32_e32 v0, s44, v160
	v_add_u32_e32 v6, v0, v161
	ds_read_b128 v[2:5], v6
	ds_read_b128 v[6:9], v6 offset:8192
	v_add_u32_e32 v200, v0, v162
	ds_read_b128 v[192:195], v200
	ds_read_b128 v[196:199], v200 offset:8192
	v_and_b32_e32 v15, 64, v234
	v_xor_b32_e32 v14, 32, v234
	v_add_u32_e32 v15, 64, v15
	s_waitcnt lgkmcnt(3)
	v_mfma_f32_32x32x16_bf16 v[96:111], v[2:5], v[112:115], v[96:111]
	v_cmp_lt_i32_e32 vcc, v14, v15
	s_nop 1
	v_cndmask_b32_e32 v14, v234, v14, vcc
	v_lshlrev_b32_e32 v14, 2, v14
	s_waitcnt lgkmcnt(2)
	v_mfma_f32_32x32x16_bf16 v[80:95], v[6:9], v[112:115], v[80:95]
	v_add_u32_e32 v6, v0, v163
	ds_read_b128 v[2:5], v6
	ds_read_b128 v[6:9], v6 offset:8192
	s_waitcnt lgkmcnt(3)
	v_mfma_f32_32x32x16_bf16 v[96:111], v[192:195], v[116:119], v[96:111]
	s_waitcnt lgkmcnt(2)
	v_mfma_f32_32x32x16_bf16 v[80:95], v[196:199], v[116:119], v[80:95]
	v_add_u32_e32 v200, v0, v164
	ds_read_b128 v[192:195], v200
	ds_read_b128 v[196:199], v200 offset:8192
	s_waitcnt lgkmcnt(3)
	v_mfma_f32_32x32x16_bf16 v[96:111], v[2:5], v[120:123], v[96:111]
	s_waitcnt lgkmcnt(2)
	v_mfma_f32_32x32x16_bf16 v[80:95], v[6:9], v[120:123], v[80:95]
	v_add_u32_e32 v6, v0, v165
	ds_read_b128 v[2:5], v6
	ds_read_b128 v[6:9], v6 offset:8192
	s_waitcnt lgkmcnt(3)
	v_mfma_f32_32x32x16_bf16 v[96:111], v[192:195], v[124:127], v[96:111]
	s_waitcnt lgkmcnt(2)
	v_mfma_f32_32x32x16_bf16 v[80:95], v[196:199], v[124:127], v[80:95]
	v_add_u32_e32 v200, v0, v166
	ds_read_b128 v[192:195], v200
	ds_read_b128 v[196:199], v200 offset:8192
	s_waitcnt lgkmcnt(3)
	v_mfma_f32_32x32x16_bf16 v[96:111], v[2:5], v[128:131], v[96:111]
	s_waitcnt lgkmcnt(2)
	v_mfma_f32_32x32x16_bf16 v[80:95], v[6:9], v[128:131], v[80:95]
	v_add_u32_e32 v6, v0, v167
	ds_read_b128 v[2:5], v6
	ds_read_b128 v[6:9], v6 offset:8192
	s_waitcnt lgkmcnt(3)
	v_mfma_f32_32x32x16_bf16 v[96:111], v[192:195], v[132:135], v[96:111]
	s_waitcnt lgkmcnt(2)
	v_mfma_f32_32x32x16_bf16 v[80:95], v[196:199], v[132:135], v[80:95]
	v_add_u32_e32 v200, v0, v168
	ds_read_b128 v[192:195], v200
	ds_read_b128 v[196:199], v200 offset:8192
	s_waitcnt lgkmcnt(3)
	v_mfma_f32_32x32x16_bf16 v[96:111], v[2:5], v[136:139], v[96:111]
	s_waitcnt lgkmcnt(2)
	v_mfma_f32_32x32x16_bf16 v[80:95], v[6:9], v[136:139], v[80:95]
	s_waitcnt lgkmcnt(1)
	v_mfma_f32_32x32x16_bf16 v[96:111], v[192:195], v[140:143], v[96:111]
	s_waitcnt lgkmcnt(0)
	v_mfma_f32_32x32x16_bf16 v[80:95], v[196:199], v[140:143], v[80:95]
	v_add_u32_e32 v201, s44, v169
	v_add_u32_e32 v202, s44, v170
	v_add_u32_e32 v203, s44, v171
	v_add_u32_e32 v204, s44, v172
	ds_read_b64_tr_b16 v[192:193], v201 offset:16384
	ds_read_b64_tr_b16 v[194:195], v202 offset:2048
	ds_read_b64_tr_b16 v[196:197], v203 offset:16384
	ds_read_b64_tr_b16 v[198:199], v204 offset:2048
	v_add_u32_e32 v2, s44, v173
	v_add_u32_e32 v3, s44, v174
	v_add_u32_e32 v4, s44, v175
	v_add_u32_e32 v5, s44, v176
	v_max_f32_e32 v15, v96, v80
	v_max3_f32 v15, v15, v97, v81
	v_max3_f32 v15, v15, v98, v82
	v_max3_f32 v15, v15, v99, v83
	v_max3_f32 v15, v15, v100, v84
	v_max3_f32 v15, v15, v101, v85
	v_max3_f32 v15, v15, v102, v86
	v_max3_f32 v15, v15, v103, v87
	v_max3_f32 v15, v15, v104, v88
	v_max3_f32 v15, v15, v105, v89
	v_max3_f32 v15, v15, v106, v90
	v_max3_f32 v15, v15, v107, v91
	v_max3_f32 v15, v15, v108, v92
	v_max3_f32 v15, v15, v109, v93
	v_max3_f32 v15, v15, v110, v94
	v_max3_f32 v15, v15, v111, v95
	v_mul_f32_e64 v15, v15, s20
	ds_bpermute_b32 v14, v14, v15
	s_waitcnt lgkmcnt(0)
	v_max3_f32 v14, v181, v15, v14
	v_sub_f32_e32 v0, v181, v14
	v_exp_f32_e32 v0, v0
	s_nop 0
	v_cmp_neq_f32_e32 vcc, 1.0, v0
	s_cbranch_vccz .LBB0_239
	v_pk_mul_f32 v[78:79], v[78:79], v[0:1] op_sel_hi:[1,0]
	v_pk_mul_f32 v[76:77], v[76:77], v[0:1] op_sel_hi:[1,0]
	v_pk_mul_f32 v[74:75], v[74:75], v[0:1] op_sel_hi:[1,0]
	v_pk_mul_f32 v[72:73], v[72:73], v[0:1] op_sel_hi:[1,0]
	v_pk_mul_f32 v[70:71], v[70:71], v[0:1] op_sel_hi:[1,0]
	v_pk_mul_f32 v[68:69], v[68:69], v[0:1] op_sel_hi:[1,0]
	v_pk_mul_f32 v[66:67], v[66:67], v[0:1] op_sel_hi:[1,0]
	v_pk_mul_f32 v[64:65], v[64:65], v[0:1] op_sel_hi:[1,0]
	v_pk_mul_f32 v[62:63], v[62:63], v[0:1] op_sel_hi:[1,0]
	v_pk_mul_f32 v[60:61], v[60:61], v[0:1] op_sel_hi:[1,0]
	v_pk_mul_f32 v[58:59], v[58:59], v[0:1] op_sel_hi:[1,0]
	v_pk_mul_f32 v[56:57], v[56:57], v[0:1] op_sel_hi:[1,0]
	v_pk_mul_f32 v[54:55], v[54:55], v[0:1] op_sel_hi:[1,0]
	v_pk_mul_f32 v[52:53], v[52:53], v[0:1] op_sel_hi:[1,0]
	v_pk_mul_f32 v[50:51], v[50:51], v[0:1] op_sel_hi:[1,0]
	v_pk_mul_f32 v[48:49], v[48:49], v[0:1] op_sel_hi:[1,0]
	v_pk_mul_f32 v[46:47], v[46:47], v[0:1] op_sel_hi:[1,0]
	v_pk_mul_f32 v[44:45], v[44:45], v[0:1] op_sel_hi:[1,0]
	v_pk_mul_f32 v[42:43], v[42:43], v[0:1] op_sel_hi:[1,0]
	v_pk_mul_f32 v[40:41], v[40:41], v[0:1] op_sel_hi:[1,0]
	v_pk_mul_f32 v[38:39], v[38:39], v[0:1] op_sel_hi:[1,0]
	v_pk_mul_f32 v[36:37], v[36:37], v[0:1] op_sel_hi:[1,0]
	v_pk_mul_f32 v[34:35], v[34:35], v[0:1] op_sel_hi:[1,0]
	v_pk_mul_f32 v[32:33], v[32:33], v[0:1] op_sel_hi:[1,0]
	v_pk_mul_f32 v[30:31], v[30:31], v[0:1] op_sel_hi:[1,0]
	v_pk_mul_f32 v[28:29], v[28:29], v[0:1] op_sel_hi:[1,0]
	v_pk_mul_f32 v[26:27], v[26:27], v[0:1] op_sel_hi:[1,0]
	v_pk_mul_f32 v[24:25], v[24:25], v[0:1] op_sel_hi:[1,0]
	v_pk_mul_f32 v[22:23], v[22:23], v[0:1] op_sel_hi:[1,0]
	v_pk_mul_f32 v[20:21], v[20:21], v[0:1] op_sel_hi:[1,0]
	v_pk_mul_f32 v[18:19], v[18:19], v[0:1] op_sel_hi:[1,0]
	v_pk_mul_f32 v[16:17], v[16:17], v[0:1] op_sel_hi:[1,0]
; #define LAS __attribute__((address_space(3)))
; __device__ __forceinline__ unsigned pk2(float lo, float hi) { f32x2 v = {lo, hi}; bf16x2_t b = __builtin_convertvector(v, bf16x2_t); return __builtin_bit_cast(unsigned, b); }
; #define MFMA32(a, b, c) __builtin_amdgcn_mfma_f32_32x32x16_bf16((a), (b), (c), 0, 0, 0)
; template <int KSTEPS, class Pol>
; __device__ __forceinline__ void attn_pass(LAS unsigned char* lds, const Pol& P, const bf16_t* qb, int ldq, const bf16_t* kb, int ldk, const bf16_t* vb, int ldv,
;                                           float qs, f32x16 (&O)[4], float& m, float& l) {
;     ...
;             const f32x2 nm = {-mnew, -mnew};
; #pragma unroll
;             for (int i = 0; i < 16; i += 2) { const f32x2 a = (f32x2){S0[i], S0[i + 1]} + nm, b = (f32x2){S1[i], S1[i + 1]} + nm; S0[i] = a.x; S0[i + 1] = a.y; S1[i] = b.x; S1[i + 1] = b.y; }
;         }
;         f32x2 ls2 = {0.f, 0.f};
; #pragma unroll
;         for (int s = 0; s < 4; ++s) {
;             unsigned w[4];
; #pragma unroll
;             for (int e = 0; e < 4; ++e) {
;                 const int i = 8 * (s & 1) + 2 * e;
;                 f32x2 pv;
;                 pv.x = __builtin_amdgcn_exp2f(s < 2 ? S0[i] : S1[i]); pv.y = __builtin_amdgcn_exp2f(s < 2 ? S0[i + 1] : S1[i + 1]);
;                 ls2 = ls2 + pv;
;                 w[e] = pk2(pv.x, pv.y);
;             }
;             u32x4 wv; wv.x = w[0]; wv.y = w[1]; wv.z = w[2]; wv.w = w[3];
;             pf[s] = __builtin_bit_cast(bf16x8, wv);
;         }
;         l = l * alpha + (ls2.x + ls2.y);
;     ...
;     auto pv_acc = [&](int st) __attribute__((always_inline)) {
;         LAS unsigned char* Vb = lds + st * A_STAGE;
; #pragma unroll
;         for (int s = 0; s < 4; ++s) {
; #pragma unroll
;             for (int blk = 0; blk < 4; ++blk) {
;                 const s16x4 lo = __builtin_amdgcn_ds_read_tr16_b64_v4i16((LAS s16x4*)(Vb + s * 4096 + voffs[blk][0]));
;                 const s16x4 hi = __builtin_amdgcn_ds_read_tr16_b64_v4i16((LAS s16x4*)(Vb + s * 4096 + voffs[blk][1]));
;                 const bf16x8 va = __builtin_shufflevector(lo, hi, 0, 1, 2, 3, 4, 5, 6, 7);
;                 O[blk] = MFMA32(va, pf[s], O[blk]);
;             }
;         }
.LBB0_239:
	v_pk_fma_f32 v[96:97], v[96:97], s[20:21], v[14:15] op_sel_hi:[1,0,0] neg_lo:[0,0,1] neg_hi:[0,0,1]
	v_pk_fma_f32 v[98:99], v[98:99], s[20:21], v[14:15] op_sel_hi:[1,0,0] neg_lo:[0,0,1] neg_hi:[0,0,1]
	v_pk_fma_f32 v[100:101], v[100:101], s[20:21], v[14:15] op_sel_hi:[1,0,0] neg_lo:[0,0,1] neg_hi:[0,0,1]
	v_pk_fma_f32 v[102:103], v[102:103], s[20:21], v[14:15] op_sel_hi:[1,0,0] neg_lo:[0,0,1] neg_hi:[0,0,1]
	v_exp_f32_e32 v96, v96
	v_exp_f32_e32 v97, v97
	v_exp_f32_e32 v98, v98
	v_exp_f32_e32 v99, v99
	v_exp_f32_e32 v100, v100
	v_exp_f32_e32 v101, v101
	v_exp_f32_e32 v102, v102
	v_exp_f32_e32 v103, v103
	v_pk_fma_f32 v[104:105], v[104:105], s[20:21], v[14:15] op_sel_hi:[1,0,0] neg_lo:[0,0,1] neg_hi:[0,0,1]
	v_pk_fma_f32 v[106:107], v[106:107], s[20:21], v[14:15] op_sel_hi:[1,0,0] neg_lo:[0,0,1] neg_hi:[0,0,1]
	v_cvt_pk_bf16_f32 v6, v96, v97
	v_cvt_pk_bf16_f32 v7, v98, v99
	v_cvt_pk_bf16_f32 v8, v100, v101
	v_cvt_pk_bf16_f32 v9, v102, v103
	v_pk_fma_f32 v[108:109], v[108:109], s[20:21], v[14:15] op_sel_hi:[1,0,0] neg_lo:[0,0,1] neg_hi:[0,0,1]
	v_pk_fma_f32 v[110:111], v[110:111], s[20:21], v[14:15] op_sel_hi:[1,0,0] neg_lo:[0,0,1] neg_hi:[0,0,1]
	v_pk_add_f32 v[224:225], v[96:97], v[98:99]
	s_waitcnt lgkmcnt(2)
	v_mfma_f32_32x32x16_bf16 v[64:79], v[192:195], v[6:9], v[64:79]
	ds_read_b64_tr_b16 v[192:193], v2 offset:16384
	ds_read_b64_tr_b16 v[194:195], v3 offset:2048
	v_exp_f32_e32 v104, v104
	v_exp_f32_e32 v105, v105
	v_exp_f32_e32 v106, v106
	v_exp_f32_e32 v107, v107
	v_pk_add_f32 v[224:225], v[100:101], v[224:225]
	s_waitcnt lgkmcnt(2)
	v_mfma_f32_32x32x16_bf16 v[48:63], v[196:199], v[6:9], v[48:63]
	ds_read_b64_tr_b16 v[196:197], v4 offset:16384
	ds_read_b64_tr_b16 v[198:199], v5 offset:2048
	v_exp_f32_e32 v108, v108
	v_exp_f32_e32 v109, v109
	v_exp_f32_e32 v110, v110
	v_exp_f32_e32 v111, v111
	v_pk_add_f32 v[224:225], v[102:103], v[224:225]
	s_waitcnt lgkmcnt(2)
	v_mfma_f32_32x32x16_bf16 v[32:47], v[192:195], v[6:9], v[32:47]
	ds_read_b64_tr_b16 v[192:193], v201 offset:20480
	ds_read_b64_tr_b16 v[194:195], v202 offset:6144
	v_cvt_pk_bf16_f32 v10, v104, v105
	v_cvt_pk_bf16_f32 v11, v106, v107
	v_cvt_pk_bf16_f32 v12, v108, v109
	v_cvt_pk_bf16_f32 v13, v110, v111
	v_pk_add_f32 v[224:225], v[104:105], v[224:225]
	s_waitcnt lgkmcnt(2)
	v_mfma_f32_32x32x16_bf16 v[16:31], v[196:199], v[6:9], v[16:31]
	ds_read_b64_tr_b16 v[196:197], v203 offset:20480
	ds_read_b64_tr_b16 v[198:199], v204 offset:6144
	v_pk_add_f32 v[224:225], v[106:107], v[224:225]
	v_pk_fma_f32 v[80:81], v[80:81], s[20:21], v[14:15] op_sel_hi:[1,0,0] neg_lo:[0,0,1] neg_hi:[0,0,1]
	v_pk_fma_f32 v[82:83], v[82:83], s[20:21], v[14:15] op_sel_hi:[1,0,0] neg_lo:[0,0,1] neg_hi:[0,0,1]
	v_pk_fma_f32 v[84:85], v[84:85], s[20:21], v[14:15] op_sel_hi:[1,0,0] neg_lo:[0,0,1] neg_hi:[0,0,1]
	v_pk_fma_f32 v[86:87], v[86:87], s[20:21], v[14:15] op_sel_hi:[1,0,0] neg_lo:[0,0,1] neg_hi:[0,0,1]
	s_waitcnt lgkmcnt(2)
	v_mfma_f32_32x32x16_bf16 v[64:79], v[192:195], v[10:13], v[64:79]
	ds_read_b64_tr_b16 v[192:193], v2 offset:20480
	ds_read_b64_tr_b16 v[194:195], v3 offset:6144
	v_exp_f32_e32 v80, v80
	v_exp_f32_e32 v81, v81
	v_exp_f32_e32 v82, v82
	v_exp_f32_e32 v83, v83
	v_pk_add_f32 v[224:225], v[108:109], v[224:225]
	s_waitcnt lgkmcnt(2)
	v_mfma_f32_32x32x16_bf16 v[48:63], v[196:199], v[10:13], v[48:63]
	ds_read_b64_tr_b16 v[196:197], v4 offset:20480
	ds_read_b64_tr_b16 v[198:199], v5 offset:6144
	v_exp_f32_e32 v84, v84
	v_exp_f32_e32 v85, v85
	v_exp_f32_e32 v86, v86
	v_exp_f32_e32 v87, v87
	v_pk_add_f32 v[224:225], v[110:111], v[224:225]
	s_waitcnt lgkmcnt(2)
	v_mfma_f32_32x32x16_bf16 v[32:47], v[192:195], v[10:13], v[32:47]
	ds_read_b64_tr_b16 v[192:193], v201 offset:24576
	ds_read_b64_tr_b16 v[194:195], v202 offset:10240
	v_cvt_pk_bf16_f32 v6, v80, v81
	v_cvt_pk_bf16_f32 v7, v82, v83
	v_cvt_pk_bf16_f32 v8, v84, v85
	v_cvt_pk_bf16_f32 v9, v86, v87
	v_pk_add_f32 v[224:225], v[80:81], v[224:225]
	s_waitcnt lgkmcnt(2)
	v_mfma_f32_32x32x16_bf16 v[16:31], v[196:199], v[10:13], v[16:31]
	ds_read_b64_tr_b16 v[196:197], v203 offset:24576
	ds_read_b64_tr_b16 v[198:199], v204 offset:10240
	v_pk_add_f32 v[224:225], v[82:83], v[224:225]
	v_pk_fma_f32 v[88:89], v[88:89], s[20:21], v[14:15] op_sel_hi:[1,0,0] neg_lo:[0,0,1] neg_hi:[0,0,1]
	v_pk_fma_f32 v[90:91], v[90:91], s[20:21], v[14:15] op_sel_hi:[1,0,0] neg_lo:[0,0,1] neg_hi:[0,0,1]
	v_pk_fma_f32 v[92:93], v[92:93], s[20:21], v[14:15] op_sel_hi:[1,0,0] neg_lo:[0,0,1] neg_hi:[0,0,1]
	v_pk_fma_f32 v[94:95], v[94:95], s[20:21], v[14:15] op_sel_hi:[1,0,0] neg_lo:[0,0,1] neg_hi:[0,0,1]
	s_waitcnt lgkmcnt(2)
	v_mfma_f32_32x32x16_bf16 v[64:79], v[192:195], v[6:9], v[64:79]
	ds_read_b64_tr_b16 v[192:193], v2 offset:24576
	ds_read_b64_tr_b16 v[194:195], v3 offset:10240
	v_exp_f32_e32 v88, v88
	v_exp_f32_e32 v89, v89
	v_exp_f32_e32 v90, v90
	v_exp_f32_e32 v91, v91
	v_pk_add_f32 v[224:225], v[84:85], v[224:225]
	s_waitcnt lgkmcnt(2)
	v_mfma_f32_32x32x16_bf16 v[48:63], v[196:199], v[6:9], v[48:63]
	ds_read_b64_tr_b16 v[196:197], v4 offset:24576
	ds_read_b64_tr_b16 v[198:199], v5 offset:10240
	v_exp_f32_e32 v92, v92
	v_exp_f32_e32 v93, v93
	v_exp_f32_e32 v94, v94
	v_exp_f32_e32 v95, v95
	v_pk_add_f32 v[224:225], v[86:87], v[224:225]
	s_waitcnt lgkmcnt(2)
	v_mfma_f32_32x32x16_bf16 v[32:47], v[192:195], v[6:9], v[32:47]
	ds_read_b64_tr_b16 v[192:193], v201 offset:28672
	ds_read_b64_tr_b16 v[194:195], v202 offset:14336
	v_cvt_pk_bf16_f32 v10, v88, v89
	v_cvt_pk_bf16_f32 v11, v90, v91
	v_cvt_pk_bf16_f32 v12, v92, v93
	v_cvt_pk_bf16_f32 v13, v94, v95
	v_pk_add_f32 v[224:225], v[88:89], v[224:225]
	s_waitcnt lgkmcnt(2)
	v_mfma_f32_32x32x16_bf16 v[16:31], v[196:199], v[6:9], v[16:31]
	ds_read_b64_tr_b16 v[196:197], v203 offset:28672
	ds_read_b64_tr_b16 v[198:199], v204 offset:14336
	v_pk_add_f32 v[224:225], v[90:91], v[224:225]
	s_waitcnt lgkmcnt(2)
	v_mfma_f32_32x32x16_bf16 v[64:79], v[192:195], v[10:13], v[64:79]
	ds_read_b64_tr_b16 v[192:193], v2 offset:28672
	ds_read_b64_tr_b16 v[194:195], v3 offset:14336
	v_pk_add_f32 v[224:225], v[92:93], v[224:225]
	s_waitcnt lgkmcnt(2)
	v_mfma_f32_32x32x16_bf16 v[48:63], v[196:199], v[10:13], v[48:63]
	ds_read_b64_tr_b16 v[196:197], v4 offset:28672
	ds_read_b64_tr_b16 v[198:199], v5 offset:14336
	v_pk_add_f32 v[224:225], v[94:95], v[224:225]
	s_waitcnt lgkmcnt(2)
	v_mfma_f32_32x32x16_bf16 v[32:47], v[192:195], v[10:13], v[32:47]
	v_add_f32_e32 v15, v224, v225
	s_waitcnt lgkmcnt(0)
	v_mfma_f32_32x32x16_bf16 v[16:31], v[196:199], v[10:13], v[16:31]
	v_fmac_f32_e32 v15, v180, v0
	s_nop 0
	v_mov_b32_e32 v180, v15
	s_cmp_gt_u32 s71, 4
	s_cbranch_scc0 .LBB0_241
	s_branch .LBB0_246
